# stagger of the N=1024 phases by XCD parity (blockIdx & 1) instead of (blockIdx >> 3) & 1
# speedup vs baseline: 1.0058x; 1.0058x over previous
; __device__ __forceinline__ const float* kin(int k) { KArgs p = (KArgs)__builtin_amdgcn_kernarg_segment_ptr(); asm volatile("" : "+s"(p)); return p->in[k]; }
; #define REFRESH() do { int t_ = threadIdx.x; asm volatile("" : "+v"(t_)); F.tid = t_; F.lane = t_ & 63; F.wave = __builtin_amdgcn_readfirstlane(t_ >> 6); } while (0)
; __global__ void __launch_bounds__(NWAVES * 64, 2) mk_fwd(Args args) {
;     ...
;     { pg8::Gemm g{Hb, (const bf16*)(ws + WS_W2), TP, DM, DFF}; pg8::StaticOrder S; S.init(TP, DM, F.G, (int)blockIdx.x);
;       pg8::EpiRes<true> E{kin(0), kin(1), out, XN, PARTP_, PARTS_, F.lds, kin(9)};
;       if ((blockIdx.x >> 3) & 1) { small_gemm(F, Hb, (const bf16*)(ws + WS_W2), TP, DFF, pg8::EpiRes<true>{kin(0), kin(1), out, XN, PARTP_, PARTS_, F.lds, kin(9)}); REFRESH(); pg8::gemm_phase<pg8::EpiRes<true>, pg8::StaticOrder, true, true>(F.lds, g, S, E); }
;       else { pg8::gemm_phase<pg8::EpiRes<true>, pg8::StaticOrder, true, true>(F.lds, g, S, E); REFRESH(); small_gemm(F, Hb, (const bf16*)(ws + WS_W2), TP, DFF, pg8::EpiRes<true>{kin(0), kin(1), out, XN, PARTP_, PARTS_, F.lds, kin(9)}); } }
.LBB0_65:
	s_mov_b64 s[6:7], s[0:1]
	s_load_dwordx2 s[36:37], s[6:7], 0x0
	s_mov_b64 s[6:7], s[0:1]
	s_add_u32 s16, s22, 0x1b00000
	s_addc_u32 s17, s23, 0
	s_load_dwordx2 s[42:43], s[6:7], 0x8
	s_mov_b64 s[6:7], s[0:1]
	s_add_u32 s38, s22, 0xfd80000
	s_load_dwordx2 s[40:41], s[6:7], 0x48
	s_addc_u32 s39, s23, 0
	s_add_u32 s14, s22, 0xfdc0000
	s_addc_u32 s15, s23, 0
	s_bitcmp0_b32 s2, 0
	s_mov_b64 s[6:7], -1
	s_cbranch_scc1 .LBB0_187
	s_mov_b64 s[6:7], s[0:1]
	s_mov_b64 s[8:9], s[0:1]
	s_mov_b64 s[10:11], s[0:1]
	s_cmpk_gt_i32 s33, 0xff
	s_cbranch_scc1 .LBB0_77
	s_load_dwordx2 s[46:47], s[6:7], 0x0
	s_load_dwordx2 s[48:49], s[8:9], 0x8
	s_load_dwordx2 s[12:13], s[10:11], 0x48
	s_lshl_b32 s3, s50, 4
	s_ashr_i32 s8, s50, 2
	s_and_b32 s3, s3, 48
	s_lshl_b32 s19, s8, 5
	s_waitcnt lgkmcnt(0)
	s_add_u32 s34, s48, 0xfc000000
	s_addc_u32 s35, s49, -1
	v_ashrrev_i32_e32 v1, 3, v188
	v_lshlrev_b32_e32 v2, 4, v188
	s_movk_i32 s6, 0x110
	s_cmp_lg_u64 s[22:23], 0
	v_and_b32_e32 v2, 0x70, v2
	v_and_b32_e32 v4, 15, v189
	v_mov_b32_e32 v3, 0
	v_mul_lo_u32 v5, v1, s6
	s_cselect_b64 s[10:11], -1, 0
	s_lshl_b32 s44, s8, 8
	v_lshl_add_u64 v[18:19], s[28:29], 0, v[2:3]
	v_lshl_add_u64 v[20:21], s[16:17], 0, v[2:3]
	v_or_b32_e32 v30, s3, v4
	v_add3_u32 v31, 0, v2, v5
	v_or_b32_e32 v4, s19, v4
	v_add3_u32 v34, 0, v5, v2
	s_add_i32 s44, s44, 0
	s_lshl_b32 s3, s3, 2
	v_cndmask_b32_e64 v2, 0, 1, s[10:11]
	v_lshrrev_b32_e32 v3, 2, v189
	v_mul_u32_u24_e32 v6, 0x110, v30
	v_and_b32_e32 v7, 48, v189
	v_mul_lo_u32 v4, v4, s6
	s_add_i32 s44, s44, s3
	v_cmp_ne_u32_e64 s[10:11], 1, v2
	v_mbcnt_lo_u32_b32 v2, -1, 0
	s_mov_b32 s45, 0
	v_add3_u32 v32, 0, v6, v7
	v_add3_u32 v33, 0, v4, v7
	v_cmp_gt_u32_e64 s[6:7], 16, v189
	v_cmp_gt_i32_e64 s[8:9], 64, v188
	v_lshl_add_u32 v35, v189, 2, s44
	v_lshl_add_u32 v36, v188, 2, 0
	v_and_or_b32 v37, v3, 12, s19
	s_lshl_b32 s3, s33, 2
	s_lshl_b32 s19, s18, 2
	s_movk_i32 s48, 0x4000
	s_movk_i32 s49, 0x1600
	v_mov_b32_e32 v38, s35
	v_mov_b32_e32 v39, s47
	v_mov_b32_e32 v40, s34
	v_mov_b32_e32 v41, s46
	s_movk_i32 s50, 0x1000
	v_mbcnt_hi_u32_b32 v42, -1, v2
	s_mov_b32 s51, s33
	s_branch .LBB0_70

; __device__ __forceinline__ const float* kin(int k) { KArgs p = (KArgs)__builtin_amdgcn_kernarg_segment_ptr(); asm volatile("" : "+s"(p)); return p->in[k]; }
; #define REFRESH() do { int t_ = threadIdx.x; asm volatile("" : "+v"(t_)); F.tid = t_; F.lane = t_ & 63; F.wave = __builtin_amdgcn_readfirstlane(t_ >> 6); } while (0)
; __global__ void __launch_bounds__(NWAVES * 64, 2) mk_fwd(Args args) {
;     ...
;     { pg8::Gemm g{(const bf16*)(ws + WS_MG), (const bf16*)(ws + WS_WO), TP, DM, DM}; pg8::StaticOrder S; S.init(TP, DM, F.G, (int)blockIdx.x);
;       pg8::EpiRes<false> E{out, out + (size_t)TP * DM, out, XN, PARTP_, PARTS_, F.lds, kin(16)};
;       if ((blockIdx.x >> 3) & 1) { small_gemm(F, (const bf16*)(ws + WS_MG), (const bf16*)(ws + WS_WO), TP, DM, pg8::EpiRes<false>{out, out + (size_t)TP * DM, out, XN, PARTP_, PARTS_, F.lds, kin(16)}); REFRESH(); pg8::gemm_phase<pg8::EpiRes<false>, pg8::StaticOrder, true, true>(F.lds, g, S, E); }
;       else { pg8::gemm_phase<pg8::EpiRes<false>, pg8::StaticOrder, true, true>(F.lds, g, S, E); REFRESH(); small_gemm(F, (const bf16*)(ws + WS_MG), (const bf16*)(ws + WS_WO), TP, DM, pg8::EpiRes<false>{out, out + (size_t)TP * DM, out, XN, PARTP_, PARTS_, F.lds, kin(16)}); } }
.LBB0_1300:
	s_add_u32 s16, s22, 0xdb80000
	s_addc_u32 s17, s23, 0
	s_add_u32 s36, s22, 0xe00000
	s_addc_u32 s37, s23, 0
	s_mov_b64 s[6:7], s[0:1]
	s_add_u32 s38, s22, 0xfd80000
	s_load_dwordx2 s[40:41], s[6:7], 0x80
	s_addc_u32 s39, s23, 0
	s_add_u32 s14, s22, 0xfdc0000
	s_addc_u32 s15, s23, 0
	s_bitcmp0_b32 s2, 0
	s_mov_b64 s[6:7], -1
	s_cbranch_scc1 .LBB0_1401
	s_mov_b64 s[6:7], s[0:1]
	s_cmpk_gt_i32 s33, 0xff
	s_cbranch_scc1 .LBB0_1312
	s_lshl_b32 s3, s50, 4
	s_ashr_i32 s8, s50, 2
	s_and_b32 s3, s3, 48
	s_lshl_b32 s19, s8, 5
	s_load_dwordx2 s[12:13], s[6:7], 0x80
	v_ashrrev_i32_e32 v1, 3, v188
	v_lshlrev_b32_e32 v2, 4, v188
	s_movk_i32 s6, 0x110
	s_cmp_lg_u64 s[22:23], 0
	v_and_b32_e32 v2, 0x70, v2
	v_and_b32_e32 v4, 15, v189
	v_mov_b32_e32 v3, 0
	v_mul_lo_u32 v5, v1, s6
	s_cselect_b64 s[10:11], -1, 0
	s_lshl_b32 s34, s8, 8
	s_waitcnt vmcnt(7)
	v_lshl_add_u64 v[18:19], s[16:17], 0, v[2:3]
	v_lshl_add_u64 v[20:21], s[36:37], 0, v[2:3]
	v_or_b32_e32 v28, s3, v4
	v_add3_u32 v29, 0, v2, v5
	v_or_b32_e32 v4, s19, v4
	v_add3_u32 v32, 0, v5, v2
	s_add_i32 s34, s34, 0
	s_lshl_b32 s3, s3, 2
	v_cndmask_b32_e64 v2, 0, 1, s[10:11]
	v_lshrrev_b32_e32 v3, 2, v189
	v_mul_u32_u24_e32 v6, 0x110, v28
	v_and_b32_e32 v7, 48, v189
	v_mul_lo_u32 v4, v4, s6
	s_add_i32 s34, s34, s3
	v_cmp_ne_u32_e64 s[10:11], 1, v2
	v_mbcnt_lo_u32_b32 v2, -1, 0
	s_mov_b32 s43, 0
	v_add3_u32 v30, 0, v6, v7
	v_add3_u32 v31, 0, v4, v7
	v_cmp_gt_u32_e64 s[6:7], 16, v189
	v_cmp_gt_i32_e64 s[8:9], 64, v188
	v_lshl_add_u32 v33, v189, 2, s34
	s_waitcnt vmcnt(4)
	v_lshl_add_u32 v34, v188, 2, 0
	v_and_or_b32 v35, v3, 12, s19
	s_lshl_b32 s3, s33, 2
	s_lshl_b32 s19, s18, 2
	v_mbcnt_hi_u32_b32 v36, -1, v2
	s_mov_b32 s46, s33
	s_branch .LBB0_1305

; #define VM_WAIT() asm volatile("s_waitcnt vmcnt(0)" ::: "memory")
; #define REFRESH() do { int t_ = threadIdx.x; asm volatile("" : "+v"(t_)); F.tid = t_; F.lane = t_ & 63; F.wave = __builtin_amdgcn_readfirstlane(t_ >> 6); } while (0)
; __global__ void __launch_bounds__(NWAVES * 64, 2) mk_fwd(Args args) {
;     ...
;       const bool small_first = ((blockIdx.x >> 3) & 1) != 0;
;       if (small_first) { small_gemm_dual(F, (const bf16*)(ws + WS_ZA), (const bf16*)(ws + WS_WA), (const bf16*)(ws + WS_BG), (const bf16*)(ws + WS_WB), (const bf16*)(ws + WS_SGA), (const bf16*)(ws + WS_SGB), (bf16*)(ws + WS_MG), TP); REFRESH(); }
;       { pg8::Gemm g{(const bf16*)(ws + WS_ZA), (const bf16*)(ws + WS_WA), TP, DM, DA}; pg8::StaticOrder S; S.init(TP, DM, F.G, (int)blockIdx.x);
;         pg8::EpiGate<0> E{(const bf16*)(ws + WS_SGA), (bf16*)(ws + WS_MG)}; pg8::gemm_phase<pg8::EpiGate<0>, pg8::StaticOrder, true, true>(F.lds, g, S, E); }
;       VM_WAIT();
;       { pg8::Gemm g{(const bf16*)(ws + WS_BG), (const bf16*)(ws + WS_WB), TP, DM, DA}; pg8::StaticOrder S; S.init(TP, DM, F.G, (int)blockIdx.x);
;         pg8::EpiGate<1> E{(const bf16*)(ws + WS_SGB), (bf16*)(ws + WS_MG)}; pg8::gemm_phase<pg8::EpiGate<1>, pg8::StaticOrder, true, true>(F.lds, g, S, E); }
;       if (!small_first) { REFRESH(); small_gemm_dual(F, (const bf16*)(ws + WS_ZA), (const bf16*)(ws + WS_WA), (const bf16*)(ws + WS_BG), (const bf16*)(ws + WS_WB), (const bf16*)(ws + WS_SGA), (const bf16*)(ws + WS_SGB), (bf16*)(ws + WS_MG), TP); }
.LBB0_1555:
	s_bitcmp0_b32 s2, 0
	s_cselect_b64 s[8:9], -1, 0
	s_and_b64 vcc, exec, s[8:9]
	s_cbranch_vccnz .LBB0_1560
	s_cmpk_gt_i32 s33, 0xff
	s_cbranch_scc1 .LBB0_1559
	s_add_u32 s6, s22, 0x6480000
	v_lshlrev_b32_e32 v2, 4, v188
	s_addc_u32 s7, s23, 0
	s_waitcnt vmcnt(4)
	v_and_b32_e32 v10, 0x70, v2
	v_mov_b32_e32 v11, 0
	s_add_u32 s10, s22, 0xdb80000
	v_lshl_add_u64 v[8:9], s[22:23], 0, v[10:11]
	s_mov_b64 s[12:13], 0xb980000
	s_addc_u32 s11, s23, 0
	v_and_b32_e32 v12, 15, v189
	v_lshl_add_u64 v[2:3], v[8:9], 0, s[12:13]
	s_mov_b64 s[12:13], 0xc00000
	s_lshl_b32 s3, s50, 4
	v_lshl_add_u64 v[4:5], v[8:9], 0, s[12:13]
	s_mov_b64 s[12:13], 0x9780000
	v_and_or_b32 v28, s3, 48, v12
	s_lshl_b32 s3, s50, 3
	v_lshl_add_u64 v[6:7], v[8:9], 0, s[12:13]
	s_mov_b64 s[12:13], 0xd00000
	s_andn2_b32 s3, s3, 31
	v_ashrrev_i32_e32 v1, 3, v188
	v_lshl_add_u64 v[8:9], v[8:9], 0, s[12:13]
	v_lshrrev_b32_e32 v11, 2, v189
	s_movk_i32 s12, 0x90
	v_or_b32_e32 v12, s3, v12
	v_and_or_b32 v29, v11, 12, s3
	v_mul_lo_u32 v11, v1, s12
	v_mul_u32_u24_e32 v13, 0x48, v28
	v_mul_lo_u32 v12, v12, s12
	v_add3_u32 v30, 0, v10, v11
	v_lshlrev_b32_e32 v13, 1, v13
	v_add3_u32 v31, 0, v11, v10
	v_add_u32_e32 v10, 0x900, v12
	s_add_i32 s3, 0, 0xfc00
	v_and_b32_e32 v11, 48, v189
	v_add3_u32 v32, 0, v13, v11
	v_add3_u32 v33, 0, v12, v11
	v_add3_u32 v34, s3, v11, v10
	v_add3_u32 v35, s3, v10, v11
	s_lshl_b32 s3, s33, 6
	s_lshl_b32 s12, s18, 6
	s_lshl_b32 s13, s33, 2
	s_lshl_b32 s14, s18, 2
	s_mov_b32 s15, s33

; #define REFRESH() do { int t_ = threadIdx.x; asm volatile("" : "+v"(t_)); F.tid = t_; F.lane = t_ & 63; F.wave = __builtin_amdgcn_readfirstlane(t_ >> 6); } while (0)
; __global__ void __launch_bounds__(NWAVES * 64, 2) mk_fwd(Args args) {
;     ...
;     { pg8::Gemm g{Hb, (const bf16*)(ws + WS_W2), TP, DM, DFF}; pg8::StaticOrder S; S.init(TP, DM, F.G, (int)blockIdx.x);
;       pg8::EpiRes<true> E{out, out + (size_t)TP * DM, out, nullptr, nullptr, nullptr, F.lds, nullptr};
;       if ((blockIdx.x >> 3) & 1) { small_gemm(F, Hb, (const bf16*)(ws + WS_W2), TP, DFF, pg8::EpiRes<true>{out, out + (size_t)TP * DM, out, nullptr, nullptr, nullptr, F.lds, nullptr}); REFRESH(); pg8::gemm_phase<pg8::EpiRes<true>, pg8::StaticOrder, true, true>(F.lds, g, S, E); }
;       else { pg8::gemm_phase<pg8::EpiRes<true>, pg8::StaticOrder, true, true>(F.lds, g, S, E); REFRESH(); small_gemm(F, Hb, (const bf16*)(ws + WS_W2), TP, DFF, pg8::EpiRes<true>{out, out + (size_t)TP * DM, out, nullptr, nullptr, nullptr, F.lds, nullptr}); } }
.LBB0_1873:
	s_or_b64 exec, exec, s[6:7]
	s_add_u32 s10, s22, 0x1b00000
	s_waitcnt lgkmcnt(0)
	v_mov_b32_e32 v2, v0
	s_addc_u32 s11, s23, 0
	s_barrier
	s_bitcmp0_b32 s2, 0
	v_readfirstlane_b32 s3, v2
	s_mov_b64 s[6:7], -1
	s_cbranch_scc1 .LBB0_1906
	s_cmpk_gt_i32 s33, 0xff
	s_cbranch_scc1 .LBB0_1877
	v_lshlrev_b32_e32 v3, 4, v2
	s_lshr_b32 s6, s3, 2
	s_ashr_i32 s3, s3, 3
	v_ashrrev_i32_e32 v38, 3, v2
	v_and_b32_e32 v4, 0x70, v3
	v_bfe_u32 v3, v2, 4, 2
	v_and_b32_e32 v2, 15, v2
	s_andn2_b32 s3, s3, 31
	v_mov_b32_e32 v5, 0
	v_and_or_b32 v39, s6, 48, v2
	s_movk_i32 s6, 0x110
	v_or_b32_e32 v2, s3, v2
	v_lshl_add_u64 v[26:27], s[28:29], 0, v[4:5]
	v_lshl_add_u64 v[28:29], s[10:11], 0, v[4:5]
	v_lshlrev_b32_e32 v40, 2, v3
	v_mul_lo_u32 v5, v38, s6
	v_mul_u32_u24_e32 v6, 0x110, v39
	v_lshlrev_b32_e32 v3, 4, v3
	v_mul_lo_u32 v2, v2, s6
	v_add3_u32 v41, 0, v4, v5
	v_add3_u32 v42, 0, v6, v3
	v_add3_u32 v43, 0, v2, v3
	v_add3_u32 v44, 0, v5, v4
	s_lshl_b32 s6, s33, 6
	s_lshl_b32 s7, s18, 6
	s_lshl_b32 s8, s33, 2
	s_lshl_b32 s9, s18, 2
	s_movk_i32 s12, 0x1600
	s_movk_i32 s13, 0x1000
	s_mov_b32 s14, s33
